# P4 combine loop software-pipelined: next row's 9 loads issued into a renamed register set before the current row is processed; the loop-invariant gain loads hoisted out of the loop
# speedup vs baseline: 1.0034x; 1.0034x over previous
.LBB0_1000:
	s_cmp_eq_u32 s70, 1
	s_cbranch_scc1 .Lmy_p4_done
	v_lshl_add_u32 v4, s33, 3, v0
	s_movk_i32 s0, 0x2000
	v_cmp_gt_i32_e32 vcc, s0, v4
	s_and_saveexec_b64 s[2:3], vcc
	s_cbranch_execz .LBB0_1003
	v_mbcnt_lo_u32_b32 v0, -1, 0
	v_mbcnt_hi_u32_b32 v0, -1, v0
	v_and_b32_e32 v1, 64, v0
	v_add_u32_e32 v1, 64, v1
	v_xor_b32_e32 v2, 1, v0
	v_cmp_lt_i32_e32 vcc, v2, v1
	s_lshl_b32 s4, s88, 3
	v_ashrrev_i32_e32 v5, 31, v4
	v_cndmask_b32_e32 v2, v0, v2, vcc
	v_lshlrev_b32_e32 v18, 2, v2
	v_xor_b32_e32 v2, 2, v0
	v_cmp_lt_i32_e32 vcc, v2, v1
	s_movk_i32 s0, 0x3000
	v_mad_i64_i32 v[8:9], s[0:1], v4, s0, 0
	v_cndmask_b32_e32 v2, v0, v2, vcc
	v_lshlrev_b32_e32 v19, 2, v2
	v_xor_b32_e32 v2, 4, v0
	v_cmp_lt_i32_e32 vcc, v2, v1
	s_ashr_i32 s5, s4, 31
	s_waitcnt lgkmcnt(0)
	v_lshlrev_b64 v[10:11], 11, v[4:5]
	v_cndmask_b32_e32 v2, v0, v2, vcc
	v_lshlrev_b32_e32 v20, 2, v2
	v_xor_b32_e32 v2, 8, v0
	v_cmp_lt_i32_e32 vcc, v2, v1
	v_lshlrev_b64 v[12:13], 6, v[4:5]
	s_mul_i32 s6, s88, 0x18000
	v_cndmask_b32_e32 v2, v0, v2, vcc
	v_lshlrev_b32_e32 v21, 2, v2
	v_xor_b32_e32 v2, 16, v0
	v_cmp_lt_i32_e32 vcc, v2, v1
	s_mul_hi_i32 s7, s4, 0x3000
	s_lshl_b64 s[8:9], s[4:5], 11
	v_cndmask_b32_e32 v2, v0, v2, vcc
	v_lshlrev_b32_e32 v22, 2, v2
	v_xor_b32_e32 v2, 32, v0
	v_cmp_lt_i32_e32 vcc, v2, v1
	v_mov_b32_e32 v1, 0
	v_and_or_b32 v12, v158, 60, v12
	v_cndmask_b32_e32 v0, v0, v2, vcc
	v_lshlrev_b32_e32 v23, 2, v0
	v_lshlrev_b32_e32 v0, 6, v97
	v_lshl_add_u64 v[6:7], s[62:63], 0, v[0:1]
	v_lshlrev_b32_e32 v0, 5, v97
	v_or_b32_e32 v8, v8, v0
	v_or_b32_e32 v10, v10, v0
	s_lshl_b64 s[10:11], s[4:5], 6
	s_mov_b64 s[12:13], 0
	s_mov_b64 s[14:15], 0x5c00000
	s_mov_b32 s5, 0x5c00000
	s_mov_b64 s[16:17], 0x6c00000
	s_mov_b32 s20, 0x6c00000
	s_mov_b64 s[18:19], 0x7c00000
	s_mov_b32 s21, 0x7c00000
	v_mov_b32_e32 v5, 0x358637bd
	s_mov_b32 s22, 0x800000
	s_mov_b32 s23, 0x9400000
	s_movk_i32 s24, 0x1fff
	global_load_dwordx4 v[230:233], v[6:7], off
	global_load_dwordx4 v[234:237], v[6:7], off offset:16
	global_load_dwordx4 v[238:241], v[6:7], off offset:32
	global_load_dwordx4 v[242:245], v[6:7], off offset:48
.LBB0_1002:
	v_lshl_add_u64 v[16:17], s[84:85], 0, v[10:11]
	v_add_co_u32_e64 v30, s[0:1], s5, v16
	v_lshl_add_u64 v[14:15], s[84:85], 0, v[12:13]
	s_nop 0
	v_addc_co_u32_e64 v31, s[0:1], 0, v17, s[0:1]
	v_add_co_u32_e64 v54, s[0:1], s20, v16
	v_lshl_add_u64 v[28:29], s[84:85], 0, v[8:9]
	s_nop 0
	v_addc_co_u32_e64 v55, s[0:1], 0, v17, s[0:1]
	v_add_co_u32_e64 v58, s[0:1], s21, v16
	v_add_co_u32_e32 v48, vcc, 0x5100000, v14
	s_nop 0
	v_addc_co_u32_e64 v59, s[0:1], 0, v17, s[0:1]
	v_lshl_add_u64 v[52:53], v[16:17], 0, s[14:15]
	v_lshl_add_u64 v[50:51], v[16:17], 0, s[16:17]
	v_lshl_add_u64 v[56:57], v[16:17], 0, s[18:19]
	v_add_co_u32_e64 v16, s[0:1], s23, v28
	v_addc_co_u32_e32 v49, vcc, 0, v15, vcc
	v_addc_co_u32_e64 v17, s[0:1], 0, v29, s[0:1]
	global_load_dwordx4 v[28:31], v[30:31], off
	s_nop 0
	global_load_dwordx4 v[32:35], v[54:55], off
	global_load_dwordx4 v[36:39], v[58:59], off
	global_load_dwordx4 v[40:43], v[50:51], off offset:16
	global_load_dwordx4 v[44:47], v[56:57], off offset:16
	v_add_co_u32_e32 v50, vcc, 0x5180000, v14
	global_load_dword v64, v[48:49], off
	s_nop 0
	v_addc_co_u32_e32 v51, vcc, 0, v15, vcc
	v_add_co_u32_e32 v14, vcc, 0x5200000, v14
	v_add_u32_e32 v4, s4, v4
	s_nop 0
	v_addc_co_u32_e32 v15, vcc, 0, v15, vcc
	global_load_dword v65, v[50:51], off
	global_load_dword v66, v[14:15], off
	s_nop 0
	global_load_dwordx4 v[48:51], v[52:53], off offset:16
	v_lshl_add_u64 v[8:9], v[8:9], 0, s[6:7]
	v_lshl_add_u64 v[10:11], v[10:11], 0, s[8:9]
	v_lshl_add_u64 v[12:13], v[12:13], 0, s[10:11]
.Lmy_cmb_loop:
	v_lshl_add_u64 v[176:177], s[84:85], 0, v[10:11]
	v_add_co_u32_e64 v190, s[0:1], s5, v176
	v_lshl_add_u64 v[174:175], s[84:85], 0, v[12:13]
	s_nop 0
	v_addc_co_u32_e64 v191, s[0:1], 0, v177, s[0:1]
	v_add_co_u32_e64 v214, s[0:1], s20, v176
	v_lshl_add_u64 v[188:189], s[84:85], 0, v[8:9]
	s_nop 0
	v_addc_co_u32_e64 v215, s[0:1], 0, v177, s[0:1]
	v_add_co_u32_e64 v218, s[0:1], s21, v176
	v_add_co_u32_e32 v208, vcc, 0x5100000, v174
	s_nop 0
	v_addc_co_u32_e64 v219, s[0:1], 0, v177, s[0:1]
	v_lshl_add_u64 v[212:213], v[176:177], 0, s[14:15]
	v_lshl_add_u64 v[210:211], v[176:177], 0, s[16:17]
	v_lshl_add_u64 v[216:217], v[176:177], 0, s[18:19]
	v_add_co_u32_e64 v176, s[0:1], s23, v188
	v_addc_co_u32_e32 v209, vcc, 0, v175, vcc
	v_addc_co_u32_e64 v177, s[0:1], 0, v189, s[0:1]
	global_load_dwordx4 v[188:191], v[190:191], off
	s_nop 0
	global_load_dwordx4 v[192:195], v[214:215], off
	global_load_dwordx4 v[196:199], v[218:219], off
	global_load_dwordx4 v[200:203], v[210:211], off offset:16
	global_load_dwordx4 v[204:207], v[216:217], off offset:16
	v_add_co_u32_e32 v210, vcc, 0x5180000, v174
	global_load_dword v224, v[208:209], off
	s_nop 0
	v_addc_co_u32_e32 v211, vcc, 0, v175, vcc
	v_add_co_u32_e32 v174, vcc, 0x5200000, v174
	v_add_u32_e32 v164, s4, v4
	s_nop 0
	v_addc_co_u32_e32 v175, vcc, 0, v175, vcc
	global_load_dword v225, v[210:211], off
	global_load_dword v226, v[174:175], off
	s_nop 0
	global_load_dwordx4 v[208:211], v[212:213], off offset:16
	v_lshl_add_u64 v[168:169], v[8:9], 0, s[6:7]
	v_lshl_add_u64 v[170:171], v[10:11], 0, s[8:9]
	v_lshl_add_u64 v[172:173], v[12:13], 0, s[10:11]
	s_waitcnt vmcnt(17)
	v_mov_b32_e32 v0, v234
	v_mov_b32_e32 v1, v235
	v_mov_b32_e32 v2, v236
	v_mov_b32_e32 v3, v237
	v_mov_b32_e32 v24, v230
	v_mov_b32_e32 v25, v231
	v_mov_b32_e32 v26, v232
	v_mov_b32_e32 v27, v233
	v_lshlrev_b32_e32 v67, 16, v28
	v_and_b32_e32 v68, 0xffff0000, v28
	v_lshlrev_b32_e32 v69, 16, v29
	v_and_b32_e32 v70, 0xffff0000, v29
	v_lshlrev_b32_e32 v71, 16, v30
	v_and_b32_e32 v72, 0xffff0000, v30
	v_lshlrev_b32_e32 v73, 16, v31
	v_and_b32_e32 v74, 0xffff0000, v31
	s_waitcnt vmcnt(15)
	v_lshlrev_b32_e32 v14, 16, v39
	v_lshlrev_b32_e32 v29, 16, v32
	v_lshlrev_b32_e32 v28, 16, v36
	v_and_b32_e32 v31, 0xffff0000, v32
	v_and_b32_e32 v30, 0xffff0000, v36
	v_lshlrev_b32_e32 v52, 16, v37
	s_waitcnt vmcnt(10)
	v_max3_f32 v75, v64, v65, v66
	v_and_b32_e32 v32, 0xffff0000, v37
	v_lshlrev_b32_e32 v37, 16, v34
	v_lshlrev_b32_e32 v36, 16, v38
	v_and_b32_e32 v55, 0xffff0000, v34
	v_and_b32_e32 v54, 0xffff0000, v38
	v_and_b32_e32 v34, 0xffff0000, v39
	v_lshlrev_b32_e32 v39, 16, v40
	v_lshlrev_b32_e32 v38, 16, v44
	v_and_b32_e32 v57, 0xffff0000, v40
	v_and_b32_e32 v56, 0xffff0000, v44
	v_lshlrev_b32_e32 v58, 16, v45
	v_and_b32_e32 v40, 0xffff0000, v45
	v_lshlrev_b32_e32 v45, 16, v42
	v_lshlrev_b32_e32 v44, 16, v46
	v_and_b32_e32 v61, 0xffff0000, v42
	v_and_b32_e32 v60, 0xffff0000, v46
	v_lshlrev_b32_e32 v62, 16, v47
	v_and_b32_e32 v42, 0xffff0000, v47
	s_waitcnt vmcnt(9)
	v_lshlrev_b32_e32 v76, 16, v48
	v_and_b32_e32 v77, 0xffff0000, v48
	v_lshlrev_b32_e32 v78, 16, v49
	v_and_b32_e32 v79, 0xffff0000, v49
	v_and_b32_e32 v46, 0xffff0000, v50
	v_lshlrev_b32_e32 v47, 16, v50
	v_and_b32_e32 v48, 0xffff0000, v51
	v_lshlrev_b32_e32 v49, 16, v51
	v_sub_f32_e32 v50, v64, v75
	v_sub_f32_e32 v51, v65, v75
	v_sub_f32_e32 v64, v66, v75
	v_mul_f32_e32 v50, 0x3fb8aa3b, v50
	v_mul_f32_e32 v51, 0x3fb8aa3b, v51
	v_mul_f32_e32 v64, 0x3fb8aa3b, v64
	v_exp_f32_e32 v65, v50
	v_exp_f32_e32 v51, v51
	v_exp_f32_e32 v50, v64
	v_lshlrev_b32_e32 v59, 16, v41
	v_and_b32_e32 v41, 0xffff0000, v41
	v_add_f32_e32 v64, v65, v51
	v_add_f32_e32 v64, v50, v64
	v_div_scale_f32 v66, s[0:1], v64, v64, 1.0
	v_rcp_f32_e32 v80, v66
	v_div_scale_f32 v75, vcc, 1.0, v64, 1.0
	v_lshlrev_b32_e32 v63, 16, v43
	v_fma_f32 v81, -v66, v80, 1.0
	v_fmac_f32_e32 v80, v81, v80
	v_mul_f32_e32 v81, v75, v80
	v_fma_f32 v82, -v66, v81, v75
	v_fmac_f32_e32 v81, v82, v80
	v_fma_f32 v66, -v66, v81, v75
	v_div_fmas_f32 v66, v66, v80, v81
	v_div_fixup_f32 v64, v66, v64, 1.0
	v_mul_f32_e32 v66, v65, v64
	v_pk_mul_f32 v[50:51], v[50:51], v[64:65] op_sel_hi:[1,0]
	v_fma_f32 v65, v66, v68, 0
	v_pk_mul_f32 v[30:31], v[50:51], v[30:31]
	v_lshlrev_b32_e32 v15, 16, v35
	v_lshlrev_b32_e32 v53, 16, v33
	v_and_b32_e32 v33, 0xffff0000, v33
	v_and_b32_e32 v35, 0xffff0000, v35
	v_and_b32_e32 v43, 0xffff0000, v43
	v_fma_f32 v64, v66, v67, 0
	v_fma_f32 v67, v66, v69, 0
	v_fma_f32 v69, v66, v71, 0
	v_fma_f32 v71, v66, v73, 0
	v_fma_f32 v73, v66, v76, 0
	v_fma_f32 v76, v66, v79, 0
	v_pk_mul_f32 v[28:29], v[50:51], v[28:29]
	v_pk_mul_f32 v[40:41], v[50:51], v[40:41]
	v_pk_mul_f32 v[44:45], v[50:51], v[44:45]
	v_pk_mul_f32 v[62:63], v[50:51], v[62:63]
	v_add_f32_e32 v31, v31, v65
	v_pk_mul_f32 v[14:15], v[50:51], v[14:15]
	v_pk_mul_f32 v[52:53], v[50:51], v[52:53]
	v_pk_mul_f32 v[32:33], v[50:51], v[32:33]
	v_pk_mul_f32 v[36:37], v[50:51], v[36:37]
	v_pk_mul_f32 v[54:55], v[50:51], v[54:55]
	v_pk_mul_f32 v[34:35], v[50:51], v[34:35]
	v_pk_mul_f32 v[38:39], v[50:51], v[38:39]
	v_pk_mul_f32 v[56:57], v[50:51], v[56:57]
	v_pk_mul_f32 v[58:59], v[50:51], v[58:59]
	v_pk_mul_f32 v[60:61], v[50:51], v[60:61]
	v_pk_mul_f32 v[42:43], v[50:51], v[42:43]
	v_add_f32_e32 v29, v29, v64
	v_add_f32_e32 v41, v41, v76
	v_mov_b32_e32 v51, v45
	v_mov_b32_e32 v45, v63
	v_add_f32_e32 v63, v30, v31
	v_fma_f32 v68, v66, v70, 0
	v_add_f32_e32 v53, v53, v67
	v_mov_b32_e32 v50, v61
	v_mov_b32_e32 v61, v44
	v_mov_b32_e32 v44, v43
	v_mov_b32_e32 v43, v62
	v_add_f32_e32 v62, v28, v29
	v_add_f32_e32 v40, v40, v41
	v_mul_f32_e32 v41, v63, v63
	v_add_f32_e32 v33, v33, v68
	v_add_f32_e32 v52, v52, v53
	v_fmac_f32_e32 v41, v62, v62
	v_fma_f32 v70, v66, v72, 0
	v_add_f32_e32 v37, v37, v69
	v_add_f32_e32 v53, v32, v33
	v_fmac_f32_e32 v41, v52, v52
	v_add_f32_e32 v55, v55, v70
	v_add_f32_e32 v36, v36, v37
	v_fmac_f32_e32 v41, v53, v53
	v_fma_f32 v72, v66, v74, 0
	v_add_f32_e32 v15, v15, v71
	v_add_f32_e32 v37, v54, v55
	v_fmac_f32_e32 v41, v36, v36
	v_add_f32_e32 v35, v35, v72
	v_add_f32_e32 v54, v14, v15
	v_fmac_f32_e32 v41, v37, v37
	v_fma_f32 v74, v66, v77, 0
	v_add_f32_e32 v39, v39, v73
	v_add_f32_e32 v34, v34, v35
	v_fmac_f32_e32 v41, v54, v54
	v_fma_f32 v75, v66, v78, 0
	v_add_f32_e32 v57, v57, v74
	v_add_f32_e32 v35, v38, v39
	v_fmac_f32_e32 v41, v34, v34
	v_pk_fma_f32 v[46:47], v[66:67], v[46:47], 0 op_sel_hi:[0,1,0]
	v_add_f32_e32 v59, v59, v75
	v_add_f32_e32 v38, v56, v57
	v_fmac_f32_e32 v41, v35, v35
	v_add_f32_e32 v39, v58, v59
	v_pk_add_f32 v[14:15], v[50:51], v[46:47]
	v_fmac_f32_e32 v41, v38, v38
	v_pk_fma_f32 v[48:49], v[66:67], v[48:49], 0 op_sel_hi:[0,1,0]
	v_pk_add_f32 v[14:15], v[60:61], v[14:15]
	v_fmac_f32_e32 v41, v39, v39
	v_pk_add_f32 v[28:29], v[44:45], v[48:49]
	v_pk_mul_f32 v[30:31], v[14:15], v[14:15]
	v_fmac_f32_e32 v41, v40, v40
	v_pk_add_f32 v[28:29], v[42:43], v[28:29]
	v_add_f32_e32 v31, v31, v41
	v_pk_mul_f32 v[32:33], v[28:29], v[28:29]
	v_add_f32_e32 v30, v30, v31
	v_add_f32_e32 v30, v33, v30
	v_add_f32_e32 v30, v32, v30
	ds_bpermute_b32 v31, v18, v30
	s_waitcnt lgkmcnt(0)
	v_add_f32_e32 v30, v30, v31
	ds_bpermute_b32 v31, v19, v30
	s_waitcnt lgkmcnt(0)
	v_add_f32_e32 v30, v30, v31
	ds_bpermute_b32 v31, v20, v30
	s_waitcnt lgkmcnt(0)
	v_add_f32_e32 v30, v30, v31
	ds_bpermute_b32 v31, v21, v30
	s_waitcnt lgkmcnt(0)
	v_add_f32_e32 v30, v30, v31
	ds_bpermute_b32 v31, v22, v30
	s_waitcnt lgkmcnt(0)
	v_add_f32_e32 v30, v30, v31
	ds_bpermute_b32 v31, v23, v30
	s_waitcnt lgkmcnt(0)
	v_add_f32_e32 v30, v30, v31
	v_fmamk_f32 v30, v30, 0x3a800000, v5
	v_mul_f32_e32 v31, 0x4b800000, v30
	v_cmp_gt_f32_e32 vcc, s22, v30
	s_nop 1
	v_cndmask_b32_e32 v30, v30, v31, vcc
	v_rsq_f32_e32 v30, v30
	s_nop 0
	v_mul_f32_e32 v31, 0x45800000, v30
	v_cndmask_b32_e32 v30, v30, v31, vcc
	v_mul_f32_e32 v34, v34, v30
	v_mul_f32_e32 v31, v62, v30
	v_mul_f32_e32 v32, v63, v30
	v_mul_f32_e32 v33, v52, v30
	v_mul_f32_e32 v41, v53, v30
	v_mul_f32_e32 v36, v36, v30
	v_mul_f32_e32 v37, v37, v30
	v_mul_f32_e32 v42, v54, v30
	v_mul_f32_e32 v3, v3, v34
	v_mul_f32_e32 v24, v24, v31
	v_mul_f32_e32 v25, v25, v32
	v_mul_f32_e32 v26, v26, v33
	v_mul_f32_e32 v27, v27, v41
	v_mul_f32_e32 v31, v0, v36
	v_mul_f32_e32 v32, v1, v37
	v_mul_f32_e32 v33, v2, v42
	v_cvt_pk_bf16_f32 v0, v24, v25
	v_cvt_pk_bf16_f32 v1, v26, v27
	v_cvt_pk_bf16_f32 v2, v31, v32
	v_cvt_pk_bf16_f32 v3, v33, v3
	global_store_dwordx4 v[16:17], v[0:3], off
	s_nop 1
	v_mov_b32_e32 v0, v238
	v_mov_b32_e32 v1, v239
	v_mov_b32_e32 v2, v240
	v_mov_b32_e32 v3, v241
	s_nop 0
	v_mov_b32_e32 v24, v242
	v_mov_b32_e32 v25, v243
	v_mov_b32_e32 v26, v244
	v_mov_b32_e32 v27, v245
	v_cmp_lt_i32_e32 vcc, s24, v4
	v_mul_f32_e32 v31, v35, v30
	v_mul_f32_e32 v32, v38, v30
	v_mul_f32_e32 v33, v39, v30
	v_mul_f32_e32 v34, v40, v30
	s_or_b64 s[12:13], vcc, s[12:13]
	v_mul_f32_e32 v15, v15, v30
	v_mul_f32_e32 v14, v14, v30
	v_mul_f32_e32 v29, v29, v30
	v_mul_f32_e32 v28, v28, v30
	v_mul_f32_e32 v0, v0, v31
	v_mul_f32_e32 v1, v1, v32
	v_mul_f32_e32 v2, v2, v33
	v_mul_f32_e32 v3, v3, v34
	v_mul_f32_e32 v15, v24, v15
	v_mul_f32_e32 v14, v25, v14
	v_mul_f32_e32 v24, v26, v29
	v_mul_f32_e32 v25, v27, v28
	v_cvt_pk_bf16_f32 v0, v0, v1
	v_cvt_pk_bf16_f32 v1, v2, v3
	v_cvt_pk_bf16_f32 v2, v15, v14
	v_cvt_pk_bf16_f32 v3, v24, v25
	global_store_dwordx4 v[16:17], v[0:3], off offset:16
	s_andn2_b64 exec, exec, s[12:13]
	s_cbranch_execz .Lmy_cmb_exit
	s_waitcnt vmcnt(2)
	v_mov_b32_e32 v4, v164
	v_mov_b32_e32 v8, v168
	v_mov_b32_e32 v9, v169
	v_mov_b32_e32 v10, v170
	v_mov_b32_e32 v11, v171
	v_mov_b32_e32 v12, v172
	v_mov_b32_e32 v13, v173
	v_mov_b32_e32 v14, v174
	v_mov_b32_e32 v15, v175
	v_mov_b32_e32 v16, v176
	v_mov_b32_e32 v17, v177
	v_mov_b32_e32 v28, v188
	v_mov_b32_e32 v29, v189
	v_mov_b32_e32 v30, v190
	v_mov_b32_e32 v31, v191
	v_mov_b32_e32 v32, v192
	v_mov_b32_e32 v33, v193
	v_mov_b32_e32 v34, v194
	v_mov_b32_e32 v35, v195
	v_mov_b32_e32 v36, v196
	v_mov_b32_e32 v37, v197
	v_mov_b32_e32 v38, v198
	v_mov_b32_e32 v39, v199
	v_mov_b32_e32 v40, v200
	v_mov_b32_e32 v41, v201
	v_mov_b32_e32 v42, v202
	v_mov_b32_e32 v43, v203
	v_mov_b32_e32 v44, v204
	v_mov_b32_e32 v45, v205
	v_mov_b32_e32 v46, v206
	v_mov_b32_e32 v47, v207
	v_mov_b32_e32 v48, v208
	v_mov_b32_e32 v49, v209
	v_mov_b32_e32 v50, v210
	v_mov_b32_e32 v51, v211
	v_mov_b32_e32 v52, v212
	v_mov_b32_e32 v53, v213
	v_mov_b32_e32 v54, v214
	v_mov_b32_e32 v55, v215
	v_mov_b32_e32 v56, v216
	v_mov_b32_e32 v57, v217
	v_mov_b32_e32 v58, v218
	v_mov_b32_e32 v59, v219
	v_mov_b32_e32 v64, v224
	v_mov_b32_e32 v65, v225
	v_mov_b32_e32 v66, v226
	s_branch .Lmy_cmb_loop
.Lmy_cmb_exit:
	s_waitcnt vmcnt(0)
.LBB0_1003:
	s_or_b64 exec, exec, s[2:3]
